# PB: the 144 workgroups with only 5 tiles start ~13us late so their epilogue bursts interleave with the other workgroups' K-loops
# speedup vs baseline: 1.0034x; 1.0022x over previous
.LBB0_634:
	s_andn2_b64 vcc, exec, s[0:1]
	s_cbranch_vccnz .LBB0_726
	s_cmp_gt_i32 s21, 0
	s_mov_b64 s[0:1], -1
	s_cbranch_scc0 .LBB0_653
	s_cmp_eq_u32 s101, 0
	s_cbranch_scc1 .Lpb_nodelay
	s_cmpk_lt_u32 s43, 0x70
	s_cbranch_scc1 .Lpb_nodelay
	s_sleep 127
	s_sleep 127
	s_sleep 127
	s_sleep 127
.Lpb_nodelay:
	v_readlane_b32 s0, v251, 31
	v_mov_b32_e32 v0, v224
	v_readlane_b32 s1, v251, 32
	s_andn2_b64 vcc, exec, s[0:1]
	v_readfirstlane_b32 s5, v0
	s_cbranch_vccnz .LBB0_652
	s_waitcnt vmcnt(0)
	v_lshlrev_b32_e32 v5, 4, v0
	v_add_u32_e32 v3, 0x2000, v5
	v_ashrrev_i32_e32 v2, 31, v3
	v_lshrrev_b32_e32 v2, 22, v2
	v_add_u32_e32 v2, v3, v2
	v_ashrrev_i32_e32 v2, 10, v2
	v_mul_i32_i24_e32 v4, 0x400, v2
	v_sub_u32_e32 v3, v3, v4
	v_lshrrev_b32_e32 v4, 4, v3
	v_bitop3_b32 v4, v4, v3, 32 bitop3:0x6c
	v_ashrrev_i32_e32 v3, 31, v4
	v_lshrrev_b32_e32 v3, 26, v3
	v_add_u32_e32 v6, v4, v3
	v_lshlrev_b32_e32 v7, 3, v2
	v_ashrrev_i32_e32 v3, 6, v6
	v_and_b32_e32 v7, -16, v7
	v_add_u32_e32 v7, v3, v7
	v_and_b32_e32 v8, 3, v3
	s_mov_b32 s0, 0x1fffe0
	v_lshrrev_b32_e32 v9, 2, v7
	v_lshlrev_b32_e32 v10, 1, v7
	v_and_b32_e32 v6, 0xc0, v6
	v_and_or_b32 v8, v7, s0, v8
	v_and_b32_e32 v9, 4, v9
	v_and_b32_e32 v10, 24, v10
	v_sub_u32_e32 v4, v4, v6
	v_or3_b32 v8, v8, v9, v10
	v_lshlrev_b32_e32 v9, 5, v2
	v_ashrrev_i16_sdwa v4, v228, sext(v4) dst_sel:DWORD dst_unused:UNUSED_PAD src0_sel:DWORD src1_sel:BYTE_0
	v_and_b32_e32 v9, 32, v9
	v_bfe_i32 v4, v4, 0, 16
	v_add_lshl_u32 v6, v9, v4, 1
	v_lshl_add_u32 v146, v8, 11, v6
	v_lshl_add_u32 v148, v7, 11, v6
	v_bfe_i32 v6, v0, 27, 1
	v_lshrrev_b32_e32 v6, 22, v6
	v_add_u32_e32 v6, v5, v6
	v_and_b32_e32 v6, 0xfffffc00, v6
	v_sub_u32_e32 v5, v5, v6
	v_lshrrev_b32_e32 v6, 4, v5
	v_bitop3_b32 v7, v6, v5, 32 bitop3:0x6c
	v_ashrrev_i32_e32 v6, 31, v0
	v_lshrrev_b32_e32 v6, 26, v6
	v_ashrrev_i32_e32 v5, 31, v7
	v_add_u32_e32 v6, v0, v6
	v_lshrrev_b32_e32 v5, 26, v5
	v_ashrrev_i32_e32 v6, 6, v6
	v_add_u32_e32 v8, v7, v5
	v_lshlrev_b32_e32 v9, 3, v6
	v_ashrrev_i32_e32 v5, 6, v8
	v_and_b32_e32 v9, -16, v9
	v_add_u32_e32 v9, v5, v9
	v_and_b32_e32 v10, 3, v5
	v_lshrrev_b32_e32 v11, 2, v9
	v_lshlrev_b32_e32 v12, 1, v9
	v_and_b32_e32 v8, 0xc0, v8
	v_and_or_b32 v10, v9, s0, v10
	v_and_b32_e32 v11, 4, v11
	v_and_b32_e32 v12, 24, v12
	v_sub_u32_e32 v7, v7, v8
	s_ashr_i32 s2, s5, 6
	v_or3_b32 v10, v10, v11, v12
	v_lshlrev_b32_e32 v11, 5, v6
	v_ashrrev_i16_sdwa v7, v228, sext(v7) dst_sel:DWORD dst_unused:UNUSED_PAD src0_sel:DWORD src1_sel:BYTE_0
	s_lshl_b32 s18, s2, 10
	v_and_b32_e32 v11, 32, v11
	v_bfe_i32 v7, v7, 0, 16
	v_add_lshl_u32 v8, v11, v7, 1
	s_add_i32 s19, s18, 0
	v_readlane_b32 s0, v251, 44
	v_lshl_add_u32 v150, v10, 11, v8
	s_add_i32 m0, s19, 0x10000
	v_readlane_b32 s1, v251, 45
	v_lshl_add_u32 v152, v9, 11, v8
	s_add_i32 s38, s19, 0x2000
	s_add_i32 s39, s19, 0x4000
	s_add_i32 s44, s19, 0x6000
	s_ashr_i32 s3, s5, 8
	global_load_lds_dwordx4 v150, s[0:1]
	s_add_i32 m0, s19, 0x12000
	s_nop 0
	global_load_lds_dwordx4 v146, s[0:1]
	v_readlane_b32 s0, v251, 40
	s_mov_b32 m0, s19
	v_readlane_b32 s1, v251, 41
	s_nop 4
	global_load_lds_dwordx4 v152, s[0:1]
	s_mov_b32 m0, s38
	s_nop 0
	global_load_lds_dwordx4 v148, s[0:1]
	v_readlane_b32 s0, v251, 38
	s_add_i32 m0, s19, 0x14000
	v_readlane_b32 s1, v251, 39
	s_nop 4
	global_load_lds_dwordx4 v150, s[0:1]
	s_add_i32 m0, s19, 0x16000
	s_cmp_lg_u32 s3, 1
	global_load_lds_dwordx4 v146, s[0:1]
	v_readlane_b32 s0, v251, 42
	s_mov_b32 m0, s39
	v_readlane_b32 s1, v251, 43
	s_nop 4
	global_load_lds_dwordx4 v152, s[0:1]
	s_mov_b32 m0, s44
	s_nop 0
	global_load_lds_dwordx4 v148, s[0:1]
	s_cbranch_scc1 .LBB0_639
	s_barrier
